# independent f32 matrix-core accumulate chains interleaved (Q K^T tiles, Q S row tiles, state tiles) and substitution rows fetched in batches
# baseline (speedup 1.0000x reference)
.Ldc_b2:
	s_waitcnt lgkmcnt(0)
	s_barrier
	s_cmp_ge_u32 s60, 2
	s_cbranch_scc1 .Ldc_s2q
	s_cmp_eq_u32 s60, 1
	s_cbranch_scc1 .Ldc_s2k
	s_mov_b32 exec_hi, 0
	v_and_b32_e32 v135, 31, v221
	v_lshlrev_b32_e32 v135, 2, v135
	ds_read_b32 v10, v135 offset:57856
	ds_read_b32 v11, v135 offset:58000
	ds_read_b32 v12, v135 offset:58144
	ds_read_b32 v13, v135 offset:58288
	ds_read_b32 v14, v135 offset:58432
	ds_read_b32 v15, v135 offset:58576
	ds_read_b32 v16, v135 offset:58720
	ds_read_b32 v17, v135 offset:58864
	ds_read_b32 v18, v135 offset:59008
	ds_read_b32 v19, v135 offset:59152
	ds_read_b32 v20, v135 offset:59296
	ds_read_b32 v21, v135 offset:59440
	ds_read_b32 v22, v135 offset:59584
	ds_read_b32 v23, v135 offset:59728
	ds_read_b32 v24, v135 offset:59872
	ds_read_b32 v25, v135 offset:60016
	ds_read_b32 v26, v135 offset:60160
	ds_read_b32 v27, v135 offset:60304
	ds_read_b32 v28, v135 offset:60448
	ds_read_b32 v29, v135 offset:60592
	ds_read_b32 v30, v135 offset:60736
	ds_read_b32 v31, v135 offset:60880
	ds_read_b32 v32, v135 offset:61024
	ds_read_b32 v33, v135 offset:61168
	ds_read_b32 v34, v135 offset:61312
	ds_read_b32 v35, v135 offset:61456
	ds_read_b32 v36, v135 offset:61600
	ds_read_b32 v37, v135 offset:61744
	ds_read_b32 v38, v135 offset:61888
	ds_read_b32 v39, v135 offset:62032
	ds_read_b32 v40, v135 offset:62176
	ds_read_b32 v41, v135 offset:62320
	ds_read_b128 v[42:45], v1 offset:44032
	ds_read_b128 v[46:49], v1 offset:44048
	ds_read_b128 v[50:53], v1 offset:44064
	ds_read_b128 v[54:57], v1 offset:44080
	ds_read_b128 v[58:61], v1 offset:44096
	ds_read_b128 v[62:65], v1 offset:44112
	ds_read_b128 v[66:69], v1 offset:44128
	ds_read_b128 v[70:73], v1 offset:44144
	s_waitcnt lgkmcnt(0)
	v_fmac_f32_e32 v11, v43, v10
	v_pk_fma_f32 v[12:13], v[44:45], v[10:11], v[12:13] op_sel:[0,0,0] op_sel_hi:[1,0,1]
	v_pk_fma_f32 v[14:15], v[46:47], v[10:11], v[14:15] op_sel:[0,0,0] op_sel_hi:[1,0,1]
	v_pk_fma_f32 v[16:17], v[48:49], v[10:11], v[16:17] op_sel:[0,0,0] op_sel_hi:[1,0,1]
	v_pk_fma_f32 v[18:19], v[50:51], v[10:11], v[18:19] op_sel:[0,0,0] op_sel_hi:[1,0,1]
	v_pk_fma_f32 v[20:21], v[52:53], v[10:11], v[20:21] op_sel:[0,0,0] op_sel_hi:[1,0,1]
	v_pk_fma_f32 v[22:23], v[54:55], v[10:11], v[22:23] op_sel:[0,0,0] op_sel_hi:[1,0,1]
	v_pk_fma_f32 v[24:25], v[56:57], v[10:11], v[24:25] op_sel:[0,0,0] op_sel_hi:[1,0,1]
	v_pk_fma_f32 v[26:27], v[58:59], v[10:11], v[26:27] op_sel:[0,0,0] op_sel_hi:[1,0,1]
	v_pk_fma_f32 v[28:29], v[60:61], v[10:11], v[28:29] op_sel:[0,0,0] op_sel_hi:[1,0,1]
	v_pk_fma_f32 v[30:31], v[62:63], v[10:11], v[30:31] op_sel:[0,0,0] op_sel_hi:[1,0,1]
	v_pk_fma_f32 v[32:33], v[64:65], v[10:11], v[32:33] op_sel:[0,0,0] op_sel_hi:[1,0,1]
	v_pk_fma_f32 v[34:35], v[66:67], v[10:11], v[34:35] op_sel:[0,0,0] op_sel_hi:[1,0,1]
	v_pk_fma_f32 v[36:37], v[68:69], v[10:11], v[36:37] op_sel:[0,0,0] op_sel_hi:[1,0,1]
	v_pk_fma_f32 v[38:39], v[70:71], v[10:11], v[38:39] op_sel:[0,0,0] op_sel_hi:[1,0,1]
	v_pk_fma_f32 v[40:41], v[72:73], v[10:11], v[40:41] op_sel:[0,0,0] op_sel_hi:[1,0,1]
	ds_read_b128 v[42:45], v1 offset:44176
	ds_read_b128 v[46:49], v1 offset:44192
	ds_read_b128 v[50:53], v1 offset:44208
	ds_read_b128 v[54:57], v1 offset:44224
	ds_read_b128 v[58:61], v1 offset:44240
	ds_read_b128 v[62:65], v1 offset:44256
	ds_read_b128 v[66:69], v1 offset:44272
	ds_read_b128 v[70:73], v1 offset:44288
	s_waitcnt lgkmcnt(0)
	v_pk_fma_f32 v[12:13], v[44:45], v[10:11], v[12:13] op_sel:[0,1,0] op_sel_hi:[1,1,1]
	v_pk_fma_f32 v[14:15], v[46:47], v[10:11], v[14:15] op_sel:[0,1,0] op_sel_hi:[1,1,1]
	v_pk_fma_f32 v[16:17], v[48:49], v[10:11], v[16:17] op_sel:[0,1,0] op_sel_hi:[1,1,1]
	v_pk_fma_f32 v[18:19], v[50:51], v[10:11], v[18:19] op_sel:[0,1,0] op_sel_hi:[1,1,1]
	v_pk_fma_f32 v[20:21], v[52:53], v[10:11], v[20:21] op_sel:[0,1,0] op_sel_hi:[1,1,1]
	v_pk_fma_f32 v[22:23], v[54:55], v[10:11], v[22:23] op_sel:[0,1,0] op_sel_hi:[1,1,1]
	v_pk_fma_f32 v[24:25], v[56:57], v[10:11], v[24:25] op_sel:[0,1,0] op_sel_hi:[1,1,1]
	v_pk_fma_f32 v[26:27], v[58:59], v[10:11], v[26:27] op_sel:[0,1,0] op_sel_hi:[1,1,1]
	v_pk_fma_f32 v[28:29], v[60:61], v[10:11], v[28:29] op_sel:[0,1,0] op_sel_hi:[1,1,1]
	v_pk_fma_f32 v[30:31], v[62:63], v[10:11], v[30:31] op_sel:[0,1,0] op_sel_hi:[1,1,1]
	v_pk_fma_f32 v[32:33], v[64:65], v[10:11], v[32:33] op_sel:[0,1,0] op_sel_hi:[1,1,1]
	v_pk_fma_f32 v[34:35], v[66:67], v[10:11], v[34:35] op_sel:[0,1,0] op_sel_hi:[1,1,1]
	v_pk_fma_f32 v[36:37], v[68:69], v[10:11], v[36:37] op_sel:[0,1,0] op_sel_hi:[1,1,1]
	v_pk_fma_f32 v[38:39], v[70:71], v[10:11], v[38:39] op_sel:[0,1,0] op_sel_hi:[1,1,1]
	v_pk_fma_f32 v[40:41], v[72:73], v[10:11], v[40:41] op_sel:[0,1,0] op_sel_hi:[1,1,1]
	ds_read_b128 v[42:45], v1 offset:44320
	ds_read_b128 v[46:49], v1 offset:44336
	ds_read_b128 v[50:53], v1 offset:44352
	ds_read_b128 v[54:57], v1 offset:44368
	ds_read_b128 v[58:61], v1 offset:44384
	ds_read_b128 v[62:65], v1 offset:44400
	ds_read_b128 v[66:69], v1 offset:44416
	ds_read_b128 v[70:73], v1 offset:44432
	ds_read_b128 v[74:77], v1 offset:44480
	ds_read_b128 v[78:81], v1 offset:44496
	ds_read_b128 v[82:85], v1 offset:44512
	ds_read_b128 v[86:89], v1 offset:44528
	ds_read_b128 v[226:229], v1 offset:44544
	ds_read_b128 v[230:233], v1 offset:44560
	ds_read_b128 v[234:237], v1 offset:44576
	s_waitcnt lgkmcnt(0)
	v_fmac_f32_e32 v13, v45, v12
	v_pk_fma_f32 v[14:15], v[46:47], v[12:13], v[14:15] op_sel:[0,0,0] op_sel_hi:[1,0,1]
	v_pk_fma_f32 v[16:17], v[48:49], v[12:13], v[16:17] op_sel:[0,0,0] op_sel_hi:[1,0,1]
	v_pk_fma_f32 v[18:19], v[50:51], v[12:13], v[18:19] op_sel:[0,0,0] op_sel_hi:[1,0,1]
	v_pk_fma_f32 v[20:21], v[52:53], v[12:13], v[20:21] op_sel:[0,0,0] op_sel_hi:[1,0,1]
	v_pk_fma_f32 v[22:23], v[54:55], v[12:13], v[22:23] op_sel:[0,0,0] op_sel_hi:[1,0,1]
	v_pk_fma_f32 v[24:25], v[56:57], v[12:13], v[24:25] op_sel:[0,0,0] op_sel_hi:[1,0,1]
	v_pk_fma_f32 v[26:27], v[58:59], v[12:13], v[26:27] op_sel:[0,0,0] op_sel_hi:[1,0,1]
	v_pk_fma_f32 v[28:29], v[60:61], v[12:13], v[28:29] op_sel:[0,0,0] op_sel_hi:[1,0,1]
	v_pk_fma_f32 v[30:31], v[62:63], v[12:13], v[30:31] op_sel:[0,0,0] op_sel_hi:[1,0,1]
	v_pk_fma_f32 v[32:33], v[64:65], v[12:13], v[32:33] op_sel:[0,0,0] op_sel_hi:[1,0,1]
	v_pk_fma_f32 v[34:35], v[66:67], v[12:13], v[34:35] op_sel:[0,0,0] op_sel_hi:[1,0,1]
	v_pk_fma_f32 v[36:37], v[68:69], v[12:13], v[36:37] op_sel:[0,0,0] op_sel_hi:[1,0,1]
	v_pk_fma_f32 v[38:39], v[70:71], v[12:13], v[38:39] op_sel:[0,0,0] op_sel_hi:[1,0,1]
	v_pk_fma_f32 v[40:41], v[72:73], v[12:13], v[40:41] op_sel:[0,0,0] op_sel_hi:[1,0,1]
	v_pk_fma_f32 v[14:15], v[74:75], v[12:13], v[14:15] op_sel:[0,1,0] op_sel_hi:[1,1,1]
	v_pk_fma_f32 v[16:17], v[76:77], v[12:13], v[16:17] op_sel:[0,1,0] op_sel_hi:[1,1,1]
	v_pk_fma_f32 v[18:19], v[78:79], v[12:13], v[18:19] op_sel:[0,1,0] op_sel_hi:[1,1,1]
	v_pk_fma_f32 v[20:21], v[80:81], v[12:13], v[20:21] op_sel:[0,1,0] op_sel_hi:[1,1,1]
	v_pk_fma_f32 v[22:23], v[82:83], v[12:13], v[22:23] op_sel:[0,1,0] op_sel_hi:[1,1,1]
	v_pk_fma_f32 v[24:25], v[84:85], v[12:13], v[24:25] op_sel:[0,1,0] op_sel_hi:[1,1,1]
	v_pk_fma_f32 v[26:27], v[86:87], v[12:13], v[26:27] op_sel:[0,1,0] op_sel_hi:[1,1,1]
	v_pk_fma_f32 v[28:29], v[88:89], v[12:13], v[28:29] op_sel:[0,1,0] op_sel_hi:[1,1,1]
	v_pk_fma_f32 v[30:31], v[226:227], v[12:13], v[30:31] op_sel:[0,1,0] op_sel_hi:[1,1,1]
	v_pk_fma_f32 v[32:33], v[228:229], v[12:13], v[32:33] op_sel:[0,1,0] op_sel_hi:[1,1,1]
	v_pk_fma_f32 v[34:35], v[230:231], v[12:13], v[34:35] op_sel:[0,1,0] op_sel_hi:[1,1,1]
	v_pk_fma_f32 v[36:37], v[232:233], v[12:13], v[36:37] op_sel:[0,1,0] op_sel_hi:[1,1,1]
	v_pk_fma_f32 v[38:39], v[234:235], v[12:13], v[38:39] op_sel:[0,1,0] op_sel_hi:[1,1,1]
	v_pk_fma_f32 v[40:41], v[236:237], v[12:13], v[40:41] op_sel:[0,1,0] op_sel_hi:[1,1,1]
	ds_read_b128 v[42:45], v1 offset:44624
	ds_read_b128 v[46:49], v1 offset:44640
	ds_read_b128 v[50:53], v1 offset:44656
	ds_read_b128 v[54:57], v1 offset:44672
	ds_read_b128 v[58:61], v1 offset:44688
	ds_read_b128 v[62:65], v1 offset:44704
	ds_read_b128 v[66:69], v1 offset:44720
	ds_read_b128 v[70:73], v1 offset:44768
	ds_read_b128 v[74:77], v1 offset:44784
	ds_read_b128 v[78:81], v1 offset:44800
	ds_read_b128 v[82:85], v1 offset:44816
	ds_read_b128 v[86:89], v1 offset:44832
	ds_read_b128 v[226:229], v1 offset:44848
	ds_read_b128 v[230:233], v1 offset:44864
	s_waitcnt lgkmcnt(0)
	v_fmac_f32_e32 v15, v43, v14
	v_pk_fma_f32 v[16:17], v[44:45], v[14:15], v[16:17] op_sel:[0,0,0] op_sel_hi:[1,0,1]
	v_pk_fma_f32 v[18:19], v[46:47], v[14:15], v[18:19] op_sel:[0,0,0] op_sel_hi:[1,0,1]
	v_pk_fma_f32 v[20:21], v[48:49], v[14:15], v[20:21] op_sel:[0,0,0] op_sel_hi:[1,0,1]
	v_pk_fma_f32 v[22:23], v[50:51], v[14:15], v[22:23] op_sel:[0,0,0] op_sel_hi:[1,0,1]
	v_pk_fma_f32 v[24:25], v[52:53], v[14:15], v[24:25] op_sel:[0,0,0] op_sel_hi:[1,0,1]
	v_pk_fma_f32 v[26:27], v[54:55], v[14:15], v[26:27] op_sel:[0,0,0] op_sel_hi:[1,0,1]
	v_pk_fma_f32 v[28:29], v[56:57], v[14:15], v[28:29] op_sel:[0,0,0] op_sel_hi:[1,0,1]
	v_pk_fma_f32 v[30:31], v[58:59], v[14:15], v[30:31] op_sel:[0,0,0] op_sel_hi:[1,0,1]
	v_pk_fma_f32 v[32:33], v[60:61], v[14:15], v[32:33] op_sel:[0,0,0] op_sel_hi:[1,0,1]
	v_pk_fma_f32 v[34:35], v[62:63], v[14:15], v[34:35] op_sel:[0,0,0] op_sel_hi:[1,0,1]
	v_pk_fma_f32 v[36:37], v[64:65], v[14:15], v[36:37] op_sel:[0,0,0] op_sel_hi:[1,0,1]
	v_pk_fma_f32 v[38:39], v[66:67], v[14:15], v[38:39] op_sel:[0,0,0] op_sel_hi:[1,0,1]
	v_pk_fma_f32 v[40:41], v[68:69], v[14:15], v[40:41] op_sel:[0,0,0] op_sel_hi:[1,0,1]
	v_pk_fma_f32 v[16:17], v[72:73], v[14:15], v[16:17] op_sel:[0,1,0] op_sel_hi:[1,1,1]
	v_pk_fma_f32 v[18:19], v[74:75], v[14:15], v[18:19] op_sel:[0,1,0] op_sel_hi:[1,1,1]
	v_pk_fma_f32 v[20:21], v[76:77], v[14:15], v[20:21] op_sel:[0,1,0] op_sel_hi:[1,1,1]
	v_pk_fma_f32 v[22:23], v[78:79], v[14:15], v[22:23] op_sel:[0,1,0] op_sel_hi:[1,1,1]
	v_pk_fma_f32 v[24:25], v[80:81], v[14:15], v[24:25] op_sel:[0,1,0] op_sel_hi:[1,1,1]
	v_pk_fma_f32 v[26:27], v[82:83], v[14:15], v[26:27] op_sel:[0,1,0] op_sel_hi:[1,1,1]
	v_pk_fma_f32 v[28:29], v[84:85], v[14:15], v[28:29] op_sel:[0,1,0] op_sel_hi:[1,1,1]
	v_pk_fma_f32 v[30:31], v[86:87], v[14:15], v[30:31] op_sel:[0,1,0] op_sel_hi:[1,1,1]
	v_pk_fma_f32 v[32:33], v[88:89], v[14:15], v[32:33] op_sel:[0,1,0] op_sel_hi:[1,1,1]
	v_pk_fma_f32 v[34:35], v[226:227], v[14:15], v[34:35] op_sel:[0,1,0] op_sel_hi:[1,1,1]
	v_pk_fma_f32 v[36:37], v[228:229], v[14:15], v[36:37] op_sel:[0,1,0] op_sel_hi:[1,1,1]
	v_pk_fma_f32 v[38:39], v[230:231], v[14:15], v[38:39] op_sel:[0,1,0] op_sel_hi:[1,1,1]
	v_pk_fma_f32 v[40:41], v[232:233], v[14:15], v[40:41] op_sel:[0,1,0] op_sel_hi:[1,1,1]
	ds_read_b128 v[42:45], v1 offset:44912
	ds_read_b128 v[46:49], v1 offset:44928
	ds_read_b128 v[50:53], v1 offset:44944
	ds_read_b128 v[54:57], v1 offset:44960
	ds_read_b128 v[58:61], v1 offset:44976
	ds_read_b128 v[62:65], v1 offset:44992
	ds_read_b128 v[66:69], v1 offset:45008
	ds_read_b128 v[70:73], v1 offset:45072
	ds_read_b128 v[74:77], v1 offset:45088
	ds_read_b128 v[78:81], v1 offset:45104
	ds_read_b128 v[82:85], v1 offset:45120
	ds_read_b128 v[86:89], v1 offset:45136
	ds_read_b128 v[226:229], v1 offset:45152
	s_waitcnt lgkmcnt(0)
	v_fmac_f32_e32 v17, v45, v16
	v_pk_fma_f32 v[18:19], v[46:47], v[16:17], v[18:19] op_sel:[0,0,0] op_sel_hi:[1,0,1]
	v_pk_fma_f32 v[20:21], v[48:49], v[16:17], v[20:21] op_sel:[0,0,0] op_sel_hi:[1,0,1]
	v_pk_fma_f32 v[22:23], v[50:51], v[16:17], v[22:23] op_sel:[0,0,0] op_sel_hi:[1,0,1]
	v_pk_fma_f32 v[24:25], v[52:53], v[16:17], v[24:25] op_sel:[0,0,0] op_sel_hi:[1,0,1]
	v_pk_fma_f32 v[26:27], v[54:55], v[16:17], v[26:27] op_sel:[0,0,0] op_sel_hi:[1,0,1]
	v_pk_fma_f32 v[28:29], v[56:57], v[16:17], v[28:29] op_sel:[0,0,0] op_sel_hi:[1,0,1]
	v_pk_fma_f32 v[30:31], v[58:59], v[16:17], v[30:31] op_sel:[0,0,0] op_sel_hi:[1,0,1]
	v_pk_fma_f32 v[32:33], v[60:61], v[16:17], v[32:33] op_sel:[0,0,0] op_sel_hi:[1,0,1]
	v_pk_fma_f32 v[34:35], v[62:63], v[16:17], v[34:35] op_sel:[0,0,0] op_sel_hi:[1,0,1]
	v_pk_fma_f32 v[36:37], v[64:65], v[16:17], v[36:37] op_sel:[0,0,0] op_sel_hi:[1,0,1]
	v_pk_fma_f32 v[38:39], v[66:67], v[16:17], v[38:39] op_sel:[0,0,0] op_sel_hi:[1,0,1]
	v_pk_fma_f32 v[40:41], v[68:69], v[16:17], v[40:41] op_sel:[0,0,0] op_sel_hi:[1,0,1]
	v_pk_fma_f32 v[18:19], v[70:71], v[16:17], v[18:19] op_sel:[0,1,0] op_sel_hi:[1,1,1]
	v_pk_fma_f32 v[20:21], v[72:73], v[16:17], v[20:21] op_sel:[0,1,0] op_sel_hi:[1,1,1]
	v_pk_fma_f32 v[22:23], v[74:75], v[16:17], v[22:23] op_sel:[0,1,0] op_sel_hi:[1,1,1]
	v_pk_fma_f32 v[24:25], v[76:77], v[16:17], v[24:25] op_sel:[0,1,0] op_sel_hi:[1,1,1]
	v_pk_fma_f32 v[26:27], v[78:79], v[16:17], v[26:27] op_sel:[0,1,0] op_sel_hi:[1,1,1]
	v_pk_fma_f32 v[28:29], v[80:81], v[16:17], v[28:29] op_sel:[0,1,0] op_sel_hi:[1,1,1]
	v_pk_fma_f32 v[30:31], v[82:83], v[16:17], v[30:31] op_sel:[0,1,0] op_sel_hi:[1,1,1]
	v_pk_fma_f32 v[32:33], v[84:85], v[16:17], v[32:33] op_sel:[0,1,0] op_sel_hi:[1,1,1]
	v_pk_fma_f32 v[34:35], v[86:87], v[16:17], v[34:35] op_sel:[0,1,0] op_sel_hi:[1,1,1]
	v_pk_fma_f32 v[36:37], v[88:89], v[16:17], v[36:37] op_sel:[0,1,0] op_sel_hi:[1,1,1]
	v_pk_fma_f32 v[38:39], v[226:227], v[16:17], v[38:39] op_sel:[0,1,0] op_sel_hi:[1,1,1]
	v_pk_fma_f32 v[40:41], v[228:229], v[16:17], v[40:41] op_sel:[0,1,0] op_sel_hi:[1,1,1]
	ds_read_b128 v[42:45], v1 offset:45216
	ds_read_b128 v[46:49], v1 offset:45232
	ds_read_b128 v[50:53], v1 offset:45248
	ds_read_b128 v[54:57], v1 offset:45264
	ds_read_b128 v[58:61], v1 offset:45280
	ds_read_b128 v[62:65], v1 offset:45296
	ds_read_b128 v[66:69], v1 offset:45360
	ds_read_b128 v[70:73], v1 offset:45376
	ds_read_b128 v[74:77], v1 offset:45392
	ds_read_b128 v[78:81], v1 offset:45408
	ds_read_b128 v[82:85], v1 offset:45424
	ds_read_b128 v[86:89], v1 offset:45440
	s_waitcnt lgkmcnt(0)
	v_fmac_f32_e32 v19, v43, v18
	v_pk_fma_f32 v[20:21], v[44:45], v[18:19], v[20:21] op_sel:[0,0,0] op_sel_hi:[1,0,1]
	v_pk_fma_f32 v[22:23], v[46:47], v[18:19], v[22:23] op_sel:[0,0,0] op_sel_hi:[1,0,1]
	v_pk_fma_f32 v[24:25], v[48:49], v[18:19], v[24:25] op_sel:[0,0,0] op_sel_hi:[1,0,1]
	v_pk_fma_f32 v[26:27], v[50:51], v[18:19], v[26:27] op_sel:[0,0,0] op_sel_hi:[1,0,1]
	v_pk_fma_f32 v[28:29], v[52:53], v[18:19], v[28:29] op_sel:[0,0,0] op_sel_hi:[1,0,1]
	v_pk_fma_f32 v[30:31], v[54:55], v[18:19], v[30:31] op_sel:[0,0,0] op_sel_hi:[1,0,1]
	v_pk_fma_f32 v[32:33], v[56:57], v[18:19], v[32:33] op_sel:[0,0,0] op_sel_hi:[1,0,1]
	v_pk_fma_f32 v[34:35], v[58:59], v[18:19], v[34:35] op_sel:[0,0,0] op_sel_hi:[1,0,1]
	v_pk_fma_f32 v[36:37], v[60:61], v[18:19], v[36:37] op_sel:[0,0,0] op_sel_hi:[1,0,1]
	v_pk_fma_f32 v[38:39], v[62:63], v[18:19], v[38:39] op_sel:[0,0,0] op_sel_hi:[1,0,1]
	v_pk_fma_f32 v[40:41], v[64:65], v[18:19], v[40:41] op_sel:[0,0,0] op_sel_hi:[1,0,1]
	v_pk_fma_f32 v[20:21], v[68:69], v[18:19], v[20:21] op_sel:[0,1,0] op_sel_hi:[1,1,1]
	v_pk_fma_f32 v[22:23], v[70:71], v[18:19], v[22:23] op_sel:[0,1,0] op_sel_hi:[1,1,1]
	v_pk_fma_f32 v[24:25], v[72:73], v[18:19], v[24:25] op_sel:[0,1,0] op_sel_hi:[1,1,1]
	v_pk_fma_f32 v[26:27], v[74:75], v[18:19], v[26:27] op_sel:[0,1,0] op_sel_hi:[1,1,1]
	v_pk_fma_f32 v[28:29], v[76:77], v[18:19], v[28:29] op_sel:[0,1,0] op_sel_hi:[1,1,1]
	v_pk_fma_f32 v[30:31], v[78:79], v[18:19], v[30:31] op_sel:[0,1,0] op_sel_hi:[1,1,1]
	v_pk_fma_f32 v[32:33], v[80:81], v[18:19], v[32:33] op_sel:[0,1,0] op_sel_hi:[1,1,1]
	v_pk_fma_f32 v[34:35], v[82:83], v[18:19], v[34:35] op_sel:[0,1,0] op_sel_hi:[1,1,1]
	v_pk_fma_f32 v[36:37], v[84:85], v[18:19], v[36:37] op_sel:[0,1,0] op_sel_hi:[1,1,1]
	v_pk_fma_f32 v[38:39], v[86:87], v[18:19], v[38:39] op_sel:[0,1,0] op_sel_hi:[1,1,1]
	v_pk_fma_f32 v[40:41], v[88:89], v[18:19], v[40:41] op_sel:[0,1,0] op_sel_hi:[1,1,1]
	ds_read_b128 v[42:45], v1 offset:45504
	ds_read_b128 v[46:49], v1 offset:45520
	ds_read_b128 v[50:53], v1 offset:45536
	ds_read_b128 v[54:57], v1 offset:45552
	ds_read_b128 v[58:61], v1 offset:45568
	ds_read_b128 v[62:65], v1 offset:45584
	ds_read_b128 v[66:69], v1 offset:45664
	ds_read_b128 v[70:73], v1 offset:45680
	ds_read_b128 v[74:77], v1 offset:45696
	ds_read_b128 v[78:81], v1 offset:45712
	ds_read_b128 v[82:85], v1 offset:45728
	s_waitcnt lgkmcnt(0)
	v_fmac_f32_e32 v21, v45, v20
	v_pk_fma_f32 v[22:23], v[46:47], v[20:21], v[22:23] op_sel:[0,0,0] op_sel_hi:[1,0,1]
	v_pk_fma_f32 v[24:25], v[48:49], v[20:21], v[24:25] op_sel:[0,0,0] op_sel_hi:[1,0,1]
	v_pk_fma_f32 v[26:27], v[50:51], v[20:21], v[26:27] op_sel:[0,0,0] op_sel_hi:[1,0,1]
	v_pk_fma_f32 v[28:29], v[52:53], v[20:21], v[28:29] op_sel:[0,0,0] op_sel_hi:[1,0,1]
	v_pk_fma_f32 v[30:31], v[54:55], v[20:21], v[30:31] op_sel:[0,0,0] op_sel_hi:[1,0,1]
	v_pk_fma_f32 v[32:33], v[56:57], v[20:21], v[32:33] op_sel:[0,0,0] op_sel_hi:[1,0,1]
	v_pk_fma_f32 v[34:35], v[58:59], v[20:21], v[34:35] op_sel:[0,0,0] op_sel_hi:[1,0,1]
	v_pk_fma_f32 v[36:37], v[60:61], v[20:21], v[36:37] op_sel:[0,0,0] op_sel_hi:[1,0,1]
	v_pk_fma_f32 v[38:39], v[62:63], v[20:21], v[38:39] op_sel:[0,0,0] op_sel_hi:[1,0,1]
	v_pk_fma_f32 v[40:41], v[64:65], v[20:21], v[40:41] op_sel:[0,0,0] op_sel_hi:[1,0,1]
	v_pk_fma_f32 v[22:23], v[66:67], v[20:21], v[22:23] op_sel:[0,1,0] op_sel_hi:[1,1,1]
	v_pk_fma_f32 v[24:25], v[68:69], v[20:21], v[24:25] op_sel:[0,1,0] op_sel_hi:[1,1,1]
	v_pk_fma_f32 v[26:27], v[70:71], v[20:21], v[26:27] op_sel:[0,1,0] op_sel_hi:[1,1,1]
	v_pk_fma_f32 v[28:29], v[72:73], v[20:21], v[28:29] op_sel:[0,1,0] op_sel_hi:[1,1,1]
	v_pk_fma_f32 v[30:31], v[74:75], v[20:21], v[30:31] op_sel:[0,1,0] op_sel_hi:[1,1,1]
	v_pk_fma_f32 v[32:33], v[76:77], v[20:21], v[32:33] op_sel:[0,1,0] op_sel_hi:[1,1,1]
	v_pk_fma_f32 v[34:35], v[78:79], v[20:21], v[34:35] op_sel:[0,1,0] op_sel_hi:[1,1,1]
	v_pk_fma_f32 v[36:37], v[80:81], v[20:21], v[36:37] op_sel:[0,1,0] op_sel_hi:[1,1,1]
	v_pk_fma_f32 v[38:39], v[82:83], v[20:21], v[38:39] op_sel:[0,1,0] op_sel_hi:[1,1,1]
	v_pk_fma_f32 v[40:41], v[84:85], v[20:21], v[40:41] op_sel:[0,1,0] op_sel_hi:[1,1,1]
	ds_read_b128 v[42:45], v1 offset:45808
	ds_read_b128 v[46:49], v1 offset:45824
	ds_read_b128 v[50:53], v1 offset:45840
	ds_read_b128 v[54:57], v1 offset:45856
	ds_read_b128 v[58:61], v1 offset:45872
	ds_read_b128 v[62:65], v1 offset:45952
	ds_read_b128 v[66:69], v1 offset:45968
	ds_read_b128 v[70:73], v1 offset:45984
	ds_read_b128 v[74:77], v1 offset:46000
	ds_read_b128 v[78:81], v1 offset:46016
	s_waitcnt lgkmcnt(0)
	v_fmac_f32_e32 v23, v43, v22
	v_pk_fma_f32 v[24:25], v[44:45], v[22:23], v[24:25] op_sel:[0,0,0] op_sel_hi:[1,0,1]
	v_pk_fma_f32 v[26:27], v[46:47], v[22:23], v[26:27] op_sel:[0,0,0] op_sel_hi:[1,0,1]
	v_pk_fma_f32 v[28:29], v[48:49], v[22:23], v[28:29] op_sel:[0,0,0] op_sel_hi:[1,0,1]
	v_pk_fma_f32 v[30:31], v[50:51], v[22:23], v[30:31] op_sel:[0,0,0] op_sel_hi:[1,0,1]
	v_pk_fma_f32 v[32:33], v[52:53], v[22:23], v[32:33] op_sel:[0,0,0] op_sel_hi:[1,0,1]
	v_pk_fma_f32 v[34:35], v[54:55], v[22:23], v[34:35] op_sel:[0,0,0] op_sel_hi:[1,0,1]
	v_pk_fma_f32 v[36:37], v[56:57], v[22:23], v[36:37] op_sel:[0,0,0] op_sel_hi:[1,0,1]
	v_pk_fma_f32 v[38:39], v[58:59], v[22:23], v[38:39] op_sel:[0,0,0] op_sel_hi:[1,0,1]
	v_pk_fma_f32 v[40:41], v[60:61], v[22:23], v[40:41] op_sel:[0,0,0] op_sel_hi:[1,0,1]
	v_pk_fma_f32 v[24:25], v[64:65], v[22:23], v[24:25] op_sel:[0,1,0] op_sel_hi:[1,1,1]
	v_pk_fma_f32 v[26:27], v[66:67], v[22:23], v[26:27] op_sel:[0,1,0] op_sel_hi:[1,1,1]
	v_pk_fma_f32 v[28:29], v[68:69], v[22:23], v[28:29] op_sel:[0,1,0] op_sel_hi:[1,1,1]
	v_pk_fma_f32 v[30:31], v[70:71], v[22:23], v[30:31] op_sel:[0,1,0] op_sel_hi:[1,1,1]
	v_pk_fma_f32 v[32:33], v[72:73], v[22:23], v[32:33] op_sel:[0,1,0] op_sel_hi:[1,1,1]
	v_pk_fma_f32 v[34:35], v[74:75], v[22:23], v[34:35] op_sel:[0,1,0] op_sel_hi:[1,1,1]
	v_pk_fma_f32 v[36:37], v[76:77], v[22:23], v[36:37] op_sel:[0,1,0] op_sel_hi:[1,1,1]
	v_pk_fma_f32 v[38:39], v[78:79], v[22:23], v[38:39] op_sel:[0,1,0] op_sel_hi:[1,1,1]
	v_pk_fma_f32 v[40:41], v[80:81], v[22:23], v[40:41] op_sel:[0,1,0] op_sel_hi:[1,1,1]
	ds_read_b128 v[42:45], v1 offset:46096
	ds_read_b128 v[46:49], v1 offset:46112
	ds_read_b128 v[50:53], v1 offset:46128
	ds_read_b128 v[54:57], v1 offset:46144
	ds_read_b128 v[58:61], v1 offset:46160
	ds_read_b128 v[62:65], v1 offset:46256
	ds_read_b128 v[66:69], v1 offset:46272
	ds_read_b128 v[70:73], v1 offset:46288
	ds_read_b128 v[74:77], v1 offset:46304
	s_waitcnt lgkmcnt(0)
	v_fmac_f32_e32 v25, v45, v24
	v_pk_fma_f32 v[26:27], v[46:47], v[24:25], v[26:27] op_sel:[0,0,0] op_sel_hi:[1,0,1]
	v_pk_fma_f32 v[28:29], v[48:49], v[24:25], v[28:29] op_sel:[0,0,0] op_sel_hi:[1,0,1]
	v_pk_fma_f32 v[30:31], v[50:51], v[24:25], v[30:31] op_sel:[0,0,0] op_sel_hi:[1,0,1]
	v_pk_fma_f32 v[32:33], v[52:53], v[24:25], v[32:33] op_sel:[0,0,0] op_sel_hi:[1,0,1]
	v_pk_fma_f32 v[34:35], v[54:55], v[24:25], v[34:35] op_sel:[0,0,0] op_sel_hi:[1,0,1]
	v_pk_fma_f32 v[36:37], v[56:57], v[24:25], v[36:37] op_sel:[0,0,0] op_sel_hi:[1,0,1]
	v_pk_fma_f32 v[38:39], v[58:59], v[24:25], v[38:39] op_sel:[0,0,0] op_sel_hi:[1,0,1]
	v_pk_fma_f32 v[40:41], v[60:61], v[24:25], v[40:41] op_sel:[0,0,0] op_sel_hi:[1,0,1]
	v_pk_fma_f32 v[26:27], v[62:63], v[24:25], v[26:27] op_sel:[0,1,0] op_sel_hi:[1,1,1]
	v_pk_fma_f32 v[28:29], v[64:65], v[24:25], v[28:29] op_sel:[0,1,0] op_sel_hi:[1,1,1]
	v_pk_fma_f32 v[30:31], v[66:67], v[24:25], v[30:31] op_sel:[0,1,0] op_sel_hi:[1,1,1]
	v_pk_fma_f32 v[32:33], v[68:69], v[24:25], v[32:33] op_sel:[0,1,0] op_sel_hi:[1,1,1]
	v_pk_fma_f32 v[34:35], v[70:71], v[24:25], v[34:35] op_sel:[0,1,0] op_sel_hi:[1,1,1]
	v_pk_fma_f32 v[36:37], v[72:73], v[24:25], v[36:37] op_sel:[0,1,0] op_sel_hi:[1,1,1]
	v_pk_fma_f32 v[38:39], v[74:75], v[24:25], v[38:39] op_sel:[0,1,0] op_sel_hi:[1,1,1]
	v_pk_fma_f32 v[40:41], v[76:77], v[24:25], v[40:41] op_sel:[0,1,0] op_sel_hi:[1,1,1]
	ds_read_b128 v[42:45], v1 offset:46400
	ds_read_b128 v[46:49], v1 offset:46416
	ds_read_b128 v[50:53], v1 offset:46432
	ds_read_b128 v[54:57], v1 offset:46448
	ds_read_b128 v[58:61], v1 offset:46544
	ds_read_b128 v[62:65], v1 offset:46560
	ds_read_b128 v[66:69], v1 offset:46576
	ds_read_b128 v[70:73], v1 offset:46592
	ds_read_b128 v[74:77], v1 offset:46688
	ds_read_b128 v[78:81], v1 offset:46704
	ds_read_b128 v[82:85], v1 offset:46720
	ds_read_b128 v[86:89], v1 offset:46736
	ds_read_b128 v[226:229], v1 offset:46848
	ds_read_b128 v[230:233], v1 offset:46864
	ds_read_b128 v[234:237], v1 offset:46880
	s_waitcnt lgkmcnt(0)
	v_fmac_f32_e32 v27, v43, v26
	v_pk_fma_f32 v[28:29], v[44:45], v[26:27], v[28:29] op_sel:[0,0,0] op_sel_hi:[1,0,1]
	v_pk_fma_f32 v[30:31], v[46:47], v[26:27], v[30:31] op_sel:[0,0,0] op_sel_hi:[1,0,1]
	v_pk_fma_f32 v[32:33], v[48:49], v[26:27], v[32:33] op_sel:[0,0,0] op_sel_hi:[1,0,1]
	v_pk_fma_f32 v[34:35], v[50:51], v[26:27], v[34:35] op_sel:[0,0,0] op_sel_hi:[1,0,1]
	v_pk_fma_f32 v[36:37], v[52:53], v[26:27], v[36:37] op_sel:[0,0,0] op_sel_hi:[1,0,1]
	v_pk_fma_f32 v[38:39], v[54:55], v[26:27], v[38:39] op_sel:[0,0,0] op_sel_hi:[1,0,1]
	v_pk_fma_f32 v[40:41], v[56:57], v[26:27], v[40:41] op_sel:[0,0,0] op_sel_hi:[1,0,1]
	v_pk_fma_f32 v[28:29], v[60:61], v[26:27], v[28:29] op_sel:[0,1,0] op_sel_hi:[1,1,1]
	v_pk_fma_f32 v[30:31], v[62:63], v[26:27], v[30:31] op_sel:[0,1,0] op_sel_hi:[1,1,1]
	v_pk_fma_f32 v[32:33], v[64:65], v[26:27], v[32:33] op_sel:[0,1,0] op_sel_hi:[1,1,1]
	v_pk_fma_f32 v[34:35], v[66:67], v[26:27], v[34:35] op_sel:[0,1,0] op_sel_hi:[1,1,1]
	v_pk_fma_f32 v[36:37], v[68:69], v[26:27], v[36:37] op_sel:[0,1,0] op_sel_hi:[1,1,1]
	v_pk_fma_f32 v[38:39], v[70:71], v[26:27], v[38:39] op_sel:[0,1,0] op_sel_hi:[1,1,1]
	v_pk_fma_f32 v[40:41], v[72:73], v[26:27], v[40:41] op_sel:[0,1,0] op_sel_hi:[1,1,1]
	v_fmac_f32_e32 v29, v77, v28
	v_pk_fma_f32 v[30:31], v[78:79], v[28:29], v[30:31] op_sel:[0,0,0] op_sel_hi:[1,0,1]
	v_pk_fma_f32 v[32:33], v[80:81], v[28:29], v[32:33] op_sel:[0,0,0] op_sel_hi:[1,0,1]
	v_pk_fma_f32 v[34:35], v[82:83], v[28:29], v[34:35] op_sel:[0,0,0] op_sel_hi:[1,0,1]
	v_pk_fma_f32 v[36:37], v[84:85], v[28:29], v[36:37] op_sel:[0,0,0] op_sel_hi:[1,0,1]
	v_pk_fma_f32 v[38:39], v[86:87], v[28:29], v[38:39] op_sel:[0,0,0] op_sel_hi:[1,0,1]
	v_pk_fma_f32 v[40:41], v[88:89], v[28:29], v[40:41] op_sel:[0,0,0] op_sel_hi:[1,0,1]
	v_pk_fma_f32 v[30:31], v[226:227], v[28:29], v[30:31] op_sel:[0,1,0] op_sel_hi:[1,1,1]
	v_pk_fma_f32 v[32:33], v[228:229], v[28:29], v[32:33] op_sel:[0,1,0] op_sel_hi:[1,1,1]
	v_pk_fma_f32 v[34:35], v[230:231], v[28:29], v[34:35] op_sel:[0,1,0] op_sel_hi:[1,1,1]
	v_pk_fma_f32 v[36:37], v[232:233], v[28:29], v[36:37] op_sel:[0,1,0] op_sel_hi:[1,1,1]
	v_pk_fma_f32 v[38:39], v[234:235], v[28:29], v[38:39] op_sel:[0,1,0] op_sel_hi:[1,1,1]
	v_pk_fma_f32 v[40:41], v[236:237], v[28:29], v[40:41] op_sel:[0,1,0] op_sel_hi:[1,1,1]
	ds_read_b128 v[42:45], v1 offset:46992
	ds_read_b128 v[46:49], v1 offset:47008
	ds_read_b128 v[50:53], v1 offset:47024
	ds_read_b128 v[54:57], v1 offset:47136
	ds_read_b128 v[58:61], v1 offset:47152
	ds_read_b128 v[62:65], v1 offset:47168
	ds_read_b128 v[66:69], v1 offset:47280
	ds_read_b128 v[70:73], v1 offset:47296
	ds_read_b128 v[74:77], v1 offset:47312
	ds_read_b128 v[78:81], v1 offset:47440
	ds_read_b128 v[82:85], v1 offset:47456
	ds_read_b128 v[86:89], v1 offset:47584
	ds_read_b128 v[226:229], v1 offset:47600
	ds_read_b128 v[230:233], v1 offset:47728
	ds_read_b128 v[234:237], v1 offset:47744
	s_waitcnt lgkmcnt(0)
	v_fmac_f32_e32 v31, v43, v30
	v_pk_fma_f32 v[32:33], v[44:45], v[30:31], v[32:33] op_sel:[0,0,0] op_sel_hi:[1,0,1]
	v_pk_fma_f32 v[34:35], v[46:47], v[30:31], v[34:35] op_sel:[0,0,0] op_sel_hi:[1,0,1]
	v_pk_fma_f32 v[36:37], v[48:49], v[30:31], v[36:37] op_sel:[0,0,0] op_sel_hi:[1,0,1]
	v_pk_fma_f32 v[38:39], v[50:51], v[30:31], v[38:39] op_sel:[0,0,0] op_sel_hi:[1,0,1]
	v_pk_fma_f32 v[40:41], v[52:53], v[30:31], v[40:41] op_sel:[0,0,0] op_sel_hi:[1,0,1]
	v_pk_fma_f32 v[32:33], v[56:57], v[30:31], v[32:33] op_sel:[0,1,0] op_sel_hi:[1,1,1]
	v_pk_fma_f32 v[34:35], v[58:59], v[30:31], v[34:35] op_sel:[0,1,0] op_sel_hi:[1,1,1]
	v_pk_fma_f32 v[36:37], v[60:61], v[30:31], v[36:37] op_sel:[0,1,0] op_sel_hi:[1,1,1]
	v_pk_fma_f32 v[38:39], v[62:63], v[30:31], v[38:39] op_sel:[0,1,0] op_sel_hi:[1,1,1]
	v_pk_fma_f32 v[40:41], v[64:65], v[30:31], v[40:41] op_sel:[0,1,0] op_sel_hi:[1,1,1]
	v_fmac_f32_e32 v33, v69, v32
	v_pk_fma_f32 v[34:35], v[70:71], v[32:33], v[34:35] op_sel:[0,0,0] op_sel_hi:[1,0,1]
	v_pk_fma_f32 v[36:37], v[72:73], v[32:33], v[36:37] op_sel:[0,0,0] op_sel_hi:[1,0,1]
	v_pk_fma_f32 v[38:39], v[74:75], v[32:33], v[38:39] op_sel:[0,0,0] op_sel_hi:[1,0,1]
	v_pk_fma_f32 v[40:41], v[76:77], v[32:33], v[40:41] op_sel:[0,0,0] op_sel_hi:[1,0,1]
	v_pk_fma_f32 v[34:35], v[78:79], v[32:33], v[34:35] op_sel:[0,1,0] op_sel_hi:[1,1,1]
	v_pk_fma_f32 v[36:37], v[80:81], v[32:33], v[36:37] op_sel:[0,1,0] op_sel_hi:[1,1,1]
	v_pk_fma_f32 v[38:39], v[82:83], v[32:33], v[38:39] op_sel:[0,1,0] op_sel_hi:[1,1,1]
	v_pk_fma_f32 v[40:41], v[84:85], v[32:33], v[40:41] op_sel:[0,1,0] op_sel_hi:[1,1,1]
	v_fmac_f32_e32 v35, v87, v34
	v_pk_fma_f32 v[36:37], v[88:89], v[34:35], v[36:37] op_sel:[0,0,0] op_sel_hi:[1,0,1]
	v_pk_fma_f32 v[38:39], v[226:227], v[34:35], v[38:39] op_sel:[0,0,0] op_sel_hi:[1,0,1]
	v_pk_fma_f32 v[40:41], v[228:229], v[34:35], v[40:41] op_sel:[0,0,0] op_sel_hi:[1,0,1]
	v_pk_fma_f32 v[36:37], v[232:233], v[34:35], v[36:37] op_sel:[0,1,0] op_sel_hi:[1,1,1]
	v_pk_fma_f32 v[38:39], v[234:235], v[34:35], v[38:39] op_sel:[0,1,0] op_sel_hi:[1,1,1]
	v_pk_fma_f32 v[40:41], v[236:237], v[34:35], v[40:41] op_sel:[0,1,0] op_sel_hi:[1,1,1]
	ds_read_b128 v[42:45], v1 offset:47872
	ds_read_b128 v[46:49], v1 offset:47888
	ds_read_b128 v[50:53], v1 offset:48032
	ds_read_b128 v[54:57], v1 offset:48176
	ds_read_b128 v[58:61], v1 offset:48320
	ds_read_b128 v[62:65], v1 offset:48464
	s_waitcnt lgkmcnt(0)
; __device__ __forceinline__ void dn_task(const Params& p, int l, int task, char* smem) {
;     ...
;       const int did = tid >> 2, pp = did >> 2, wh = did & 3, part = tid & 3;
;       const float* xr = (wh == 0) ? (ks + (2 * pp + 1) * 68) : (wh == 1) ? (qs + (2 * pp) * 68) : (qs + (2 * pp + 1) * 68);
;       const float* yr = (wh == 3) ? (ks + (2 * pp + 1) * 68) : (ks + (2 * pp) * 68);
;       float sdot = 0.f;
; #pragma unroll
;       for (int i = 0; i < 16; ++i) sdot += xr[part * 16 + i] * yr[part * 16 + i];
;       sdot = quad_sum(sdot);
;       if (part == 0) dots[did] = sdot;
;     }
	v_fmac_f32_e32 v37, v45, v36
	v_pk_fma_f32 v[38:39], v[46:47], v[36:37], v[38:39] op_sel:[0,0,0] op_sel_hi:[1,0,1]
	v_pk_fma_f32 v[40:41], v[48:49], v[36:37], v[40:41] op_sel:[0,0,0] op_sel_hi:[1,0,1]
	v_pk_fma_f32 v[38:39], v[50:51], v[36:37], v[38:39] op_sel:[0,1,0] op_sel_hi:[1,1,1]
	v_pk_fma_f32 v[40:41], v[52:53], v[36:37], v[40:41] op_sel:[0,1,0] op_sel_hi:[1,1,1]
	v_fmac_f32_e32 v39, v55, v38
	v_pk_fma_f32 v[40:41], v[56:57], v[38:39], v[40:41] op_sel:[0,0,0] op_sel_hi:[1,0,1]
	v_pk_fma_f32 v[40:41], v[60:61], v[38:39], v[40:41] op_sel:[0,1,0] op_sel_hi:[1,1,1]
	v_fmac_f32_e32 v41, v65, v40
	ds_write_b32 v135, v10 offset:57856
	ds_write_b32 v135, v11 offset:58000
	ds_write_b32 v135, v12 offset:58144
	ds_write_b32 v135, v13 offset:58288
	ds_write_b32 v135, v14 offset:58432
	ds_write_b32 v135, v15 offset:58576
	ds_write_b32 v135, v16 offset:58720
	ds_write_b32 v135, v17 offset:58864
	ds_write_b32 v135, v18 offset:59008
	ds_write_b32 v135, v19 offset:59152
	ds_write_b32 v135, v20 offset:59296
	ds_write_b32 v135, v21 offset:59440
	ds_write_b32 v135, v22 offset:59584
	ds_write_b32 v135, v23 offset:59728
	ds_write_b32 v135, v24 offset:59872
	ds_write_b32 v135, v25 offset:60016
	ds_write_b32 v135, v26 offset:60160
	ds_write_b32 v135, v27 offset:60304
	ds_write_b32 v135, v28 offset:60448
	ds_write_b32 v135, v29 offset:60592
	ds_write_b32 v135, v30 offset:60736
	ds_write_b32 v135, v31 offset:60880
	ds_write_b32 v135, v32 offset:61024
	ds_write_b32 v135, v33 offset:61168
	ds_write_b32 v135, v34 offset:61312
	ds_write_b32 v135, v35 offset:61456
	ds_write_b32 v135, v36 offset:61600
	ds_write_b32 v135, v37 offset:61744
	ds_write_b32 v135, v38 offset:61888
	ds_write_b32 v135, v39 offset:62032
	ds_write_b32 v135, v40 offset:62176
	ds_write_b32 v135, v41 offset:62320
	s_mov_b32 exec_hi, -1
	s_branch .Ldc_b3
.Ldc_s2k:
	ds_read_b128 v[10:13], v224 offset:0
	ds_read_b128 v[14:17], v224 offset:16
	ds_read_b128 v[18:21], v224 offset:32
	ds_read_b128 v[22:25], v224 offset:48
	ds_read_b128 v[26:29], v224 offset:4352
	ds_read_b128 v[30:33], v224 offset:4368
	ds_read_b128 v[34:37], v224 offset:4384
	ds_read_b128 v[38:41], v224 offset:4400
	ds_read_b128 v[42:45], v224 offset:8704
	ds_read_b128 v[46:49], v224 offset:8720
	ds_read_b128 v[50:53], v224 offset:8736
	ds_read_b128 v[54:57], v224 offset:8752
	ds_read_b128 v[66:69], v224 offset:13056
	ds_read_b128 v[70:73], v224 offset:13072
	ds_read_b128 v[74:77], v224 offset:13088
	ds_read_b128 v[78:81], v224 offset:13104
	ds_read_b32 v82, v225 offset:53248
	ds_read_b32 v83, v225 offset:53392
	ds_read_b32 v84, v225 offset:53536
	ds_read_b32 v85, v225 offset:53680
	ds_read_b32 v86, v225 offset:55552
	ds_read_b32 v87, v225 offset:55696
	ds_read_b32 v88, v225 offset:55840
	ds_read_b32 v89, v225 offset:55984
	ds_read_b32 v226, v225 offset:55616
	ds_read_b32 v227, v225 offset:55760
	ds_read_b32 v228, v225 offset:55904
	ds_read_b32 v229, v225 offset:56048
	s_waitcnt lgkmcnt(0)
	v_mfma_f32_16x16x4_f32 v[58:61], v10, v42, 0
	v_mfma_f32_16x16x4_f32 v[62:65], v26, v42, 0
	v_mfma_f32_16x16x4_f32 v[230:233], v26, v66, 0
	v_mfma_f32_16x16x4_f32 v[58:61], v11, v43, v[58:61]
	v_mfma_f32_16x16x4_f32 v[62:65], v27, v43, v[62:65]
	v_mfma_f32_16x16x4_f32 v[230:233], v27, v67, v[230:233]
	v_mfma_f32_16x16x4_f32 v[58:61], v12, v44, v[58:61]
	v_mfma_f32_16x16x4_f32 v[62:65], v28, v44, v[62:65]
	v_mfma_f32_16x16x4_f32 v[230:233], v28, v68, v[230:233]
	v_mfma_f32_16x16x4_f32 v[58:61], v13, v45, v[58:61]
	v_mfma_f32_16x16x4_f32 v[62:65], v29, v45, v[62:65]
	v_mfma_f32_16x16x4_f32 v[230:233], v29, v69, v[230:233]
	v_mfma_f32_16x16x4_f32 v[58:61], v14, v46, v[58:61]
	v_mfma_f32_16x16x4_f32 v[62:65], v30, v46, v[62:65]
	v_mfma_f32_16x16x4_f32 v[230:233], v30, v70, v[230:233]
	v_mfma_f32_16x16x4_f32 v[58:61], v15, v47, v[58:61]
	v_mfma_f32_16x16x4_f32 v[62:65], v31, v47, v[62:65]
	v_mfma_f32_16x16x4_f32 v[230:233], v31, v71, v[230:233]
	v_mfma_f32_16x16x4_f32 v[58:61], v16, v48, v[58:61]
	v_mfma_f32_16x16x4_f32 v[62:65], v32, v48, v[62:65]
	v_mfma_f32_16x16x4_f32 v[230:233], v32, v72, v[230:233]
	v_mfma_f32_16x16x4_f32 v[58:61], v17, v49, v[58:61]
	v_mfma_f32_16x16x4_f32 v[62:65], v33, v49, v[62:65]
	v_mfma_f32_16x16x4_f32 v[230:233], v33, v73, v[230:233]
	v_mfma_f32_16x16x4_f32 v[58:61], v18, v50, v[58:61]
	v_mfma_f32_16x16x4_f32 v[62:65], v34, v50, v[62:65]
	v_mfma_f32_16x16x4_f32 v[230:233], v34, v74, v[230:233]
	v_mfma_f32_16x16x4_f32 v[58:61], v19, v51, v[58:61]
	v_mfma_f32_16x16x4_f32 v[62:65], v35, v51, v[62:65]
	v_mfma_f32_16x16x4_f32 v[230:233], v35, v75, v[230:233]
	v_mfma_f32_16x16x4_f32 v[58:61], v20, v52, v[58:61]
	v_mfma_f32_16x16x4_f32 v[62:65], v36, v52, v[62:65]
	v_mfma_f32_16x16x4_f32 v[230:233], v36, v76, v[230:233]
	v_mfma_f32_16x16x4_f32 v[58:61], v21, v53, v[58:61]
	v_mfma_f32_16x16x4_f32 v[62:65], v37, v53, v[62:65]
	v_mfma_f32_16x16x4_f32 v[230:233], v37, v77, v[230:233]
	v_mfma_f32_16x16x4_f32 v[58:61], v22, v54, v[58:61]
	v_mfma_f32_16x16x4_f32 v[62:65], v38, v54, v[62:65]
	v_mfma_f32_16x16x4_f32 v[230:233], v38, v78, v[230:233]
	v_mfma_f32_16x16x4_f32 v[58:61], v23, v55, v[58:61]
	v_mfma_f32_16x16x4_f32 v[62:65], v39, v55, v[62:65]
	v_mfma_f32_16x16x4_f32 v[230:233], v39, v79, v[230:233]
	v_mfma_f32_16x16x4_f32 v[58:61], v24, v56, v[58:61]
	v_mfma_f32_16x16x4_f32 v[62:65], v40, v56, v[62:65]
	v_mfma_f32_16x16x4_f32 v[230:233], v40, v80, v[230:233]
	v_mfma_f32_16x16x4_f32 v[58:61], v25, v57, v[58:61]
	v_mfma_f32_16x16x4_f32 v[62:65], v41, v57, v[62:65]
	v_mfma_f32_16x16x4_f32 v[230:233], v41, v81, v[230:233]
	s_nop 7
	s_nop 3
	v_mul_f32_e32 v58, v58, v82
	ds_write_b32 v225, v58 offset:48640
	v_mul_f32_e32 v59, v59, v83
	ds_write_b32 v225, v59 offset:48784
	v_mul_f32_e32 v60, v60, v84
	ds_write_b32 v225, v60 offset:48928
	v_mul_f32_e32 v61, v61, v85
	ds_write_b32 v225, v61 offset:49072
	v_mul_f32_e32 v62, v62, v86
	ds_write_b32 v225, v62 offset:50944
	v_mul_f32_e32 v63, v63, v87
	ds_write_b32 v225, v63 offset:51088
	v_mul_f32_e32 v64, v64, v88
	ds_write_b32 v225, v64 offset:51232
	v_mul_f32_e32 v65, v65, v89
	ds_write_b32 v225, v65 offset:51376
	v_mul_f32_e32 v230, v230, v226
	ds_write_b32 v225, v230 offset:51008
	v_mul_f32_e32 v231, v231, v227
	ds_write_b32 v225, v231 offset:51152
	v_mul_f32_e32 v232, v232, v228
	ds_write_b32 v225, v232 offset:51296
	v_mul_f32_e32 v233, v233, v229
	ds_write_b32 v225, v233 offset:51440
	s_branch .Ldc_b3

.Ldc_q2:
	ds_read_b128 v[26:29], v224 offset:0
	ds_read_b128 v[30:33], v224 offset:16
	ds_read_b128 v[34:37], v224 offset:32
	ds_read_b128 v[38:41], v224 offset:48
	ds_read_b128 v[66:69], v224 offset:4352
	ds_read_b128 v[70:73], v224 offset:4368
	ds_read_b128 v[74:77], v224 offset:4384
	ds_read_b128 v[78:81], v224 offset:4400
	v_lshlrev_b32_e32 v245, 2, v222
	v_add_u32_e32 v245, 0x13700, v245
	ds_read_b32 v42, v245 offset:0
	ds_read_b32 v43, v245 offset:64
	s_waitcnt lgkmcnt(0)
	v_mul_f32_e32 v26, v42, v26
	v_mul_f32_e32 v66, v43, v66
	v_mul_f32_e32 v27, v42, v27
	v_mul_f32_e32 v67, v43, v67
	v_mul_f32_e32 v28, v42, v28
	v_mul_f32_e32 v68, v43, v68
	v_mul_f32_e32 v29, v42, v29
	v_mul_f32_e32 v69, v43, v69
	v_mul_f32_e32 v30, v42, v30
	v_mul_f32_e32 v70, v43, v70
	v_mul_f32_e32 v31, v42, v31
	v_mul_f32_e32 v71, v43, v71
	v_mul_f32_e32 v32, v42, v32
	v_mul_f32_e32 v72, v43, v72
	v_mul_f32_e32 v33, v42, v33
	v_mul_f32_e32 v73, v43, v73
	v_mul_f32_e32 v34, v42, v34
	v_mul_f32_e32 v74, v43, v74
	v_mul_f32_e32 v35, v42, v35
	v_mul_f32_e32 v75, v43, v75
	v_mul_f32_e32 v36, v42, v36
	v_mul_f32_e32 v76, v43, v76
	v_mul_f32_e32 v37, v42, v37
	v_mul_f32_e32 v77, v43, v77
	v_mul_f32_e32 v38, v42, v38
	v_mul_f32_e32 v78, v43, v78
	v_mul_f32_e32 v39, v42, v39
	v_mul_f32_e32 v79, v43, v79
	v_mul_f32_e32 v40, v42, v40
	v_mul_f32_e32 v80, v43, v80
	v_mul_f32_e32 v41, v42, v41
	v_mul_f32_e32 v81, v43, v81
	s_nop 1
	v_mfma_f32_16x16x4_f32 v[58:61], v26, v10, 0
	v_mfma_f32_16x16x4_f32 v[62:65], v66, v10, 0
	v_mfma_f32_16x16x4_f32 v[58:61], v27, v11, v[58:61]
	v_mfma_f32_16x16x4_f32 v[62:65], v67, v11, v[62:65]
	v_mfma_f32_16x16x4_f32 v[58:61], v28, v12, v[58:61]
	v_mfma_f32_16x16x4_f32 v[62:65], v68, v12, v[62:65]
	v_mfma_f32_16x16x4_f32 v[58:61], v29, v13, v[58:61]
	v_mfma_f32_16x16x4_f32 v[62:65], v69, v13, v[62:65]
	v_mfma_f32_16x16x4_f32 v[58:61], v30, v14, v[58:61]
	v_mfma_f32_16x16x4_f32 v[62:65], v70, v14, v[62:65]
	v_mfma_f32_16x16x4_f32 v[58:61], v31, v15, v[58:61]
	v_mfma_f32_16x16x4_f32 v[62:65], v71, v15, v[62:65]
	v_mfma_f32_16x16x4_f32 v[58:61], v32, v16, v[58:61]
	v_mfma_f32_16x16x4_f32 v[62:65], v72, v16, v[62:65]
	v_mfma_f32_16x16x4_f32 v[58:61], v33, v17, v[58:61]
	v_mfma_f32_16x16x4_f32 v[62:65], v73, v17, v[62:65]
	v_mfma_f32_16x16x4_f32 v[58:61], v34, v18, v[58:61]
	v_mfma_f32_16x16x4_f32 v[62:65], v74, v18, v[62:65]
	v_mfma_f32_16x16x4_f32 v[58:61], v35, v19, v[58:61]
	v_mfma_f32_16x16x4_f32 v[62:65], v75, v19, v[62:65]
	v_mfma_f32_16x16x4_f32 v[58:61], v36, v20, v[58:61]
	v_mfma_f32_16x16x4_f32 v[62:65], v76, v20, v[62:65]
	v_mfma_f32_16x16x4_f32 v[58:61], v37, v21, v[58:61]
	v_mfma_f32_16x16x4_f32 v[62:65], v77, v21, v[62:65]
	v_mfma_f32_16x16x4_f32 v[58:61], v38, v22, v[58:61]
	v_mfma_f32_16x16x4_f32 v[62:65], v78, v22, v[62:65]
	v_mfma_f32_16x16x4_f32 v[58:61], v39, v23, v[58:61]
	v_mfma_f32_16x16x4_f32 v[62:65], v79, v23, v[62:65]
	v_mfma_f32_16x16x4_f32 v[58:61], v40, v24, v[58:61]
	v_mfma_f32_16x16x4_f32 v[62:65], v80, v24, v[62:65]
	v_mfma_f32_16x16x4_f32 v[58:61], v41, v25, v[58:61]
	v_mfma_f32_16x16x4_f32 v[62:65], v81, v25, v[62:65]

.Ldc_s4w:
	s_and_b32 s61, s60, 1
	s_lshl_b32 s61, s61, 6
	v_mul_u32_u24_e32 v244, 0x480, v223
	v_lshl_add_u32 v244, v222, 2, v244
	v_add_u32_e32 v244, s61, v244
	ds_read_b32 v34, v244 offset:57856
	ds_read_b32 v35, v244 offset:58000
	ds_read_b32 v36, v244 offset:58144
	ds_read_b32 v37, v244 offset:58288
	ds_read_b32 v38, v244 offset:58432
	ds_read_b32 v39, v244 offset:58576
	ds_read_b32 v40, v244 offset:58720
	ds_read_b32 v41, v244 offset:58864
	v_lshlrev_b32_e32 v245, 5, v223
	v_add_u32_e32 v245, 0x13780, v245
	ds_read_b128 v[42:45], v245
	ds_read_b128 v[46:49], v245 offset:16
	v_mov_b32_e32 v79, 0x1377c
	ds_read_b32 v78, v79
	v_mul_u32_u24_e32 v246, 0x880, v223
	v_lshl_add_u32 v246, v222, 2, v246
	s_and_b32 s61, s60, 1
	s_lshl_b32 s61, s61, 6
	s_add_i32 s61, s61, 0x11600
	v_mul_u32_u24_e32 v244, 0x210, v223
	v_lshl_add_u32 v244, v222, 2, v244
	v_add_u32_e32 v244, s61, v244
	ds_read_b32 v26, v246 offset:8704
	ds_read_b32 v27, v246 offset:8976
	ds_read_b32 v28, v246 offset:9248
	ds_read_b32 v29, v246 offset:9520
	ds_read_b32 v30, v246 offset:9792
	ds_read_b32 v31, v246 offset:10064
	ds_read_b32 v32, v246 offset:10336
	ds_read_b32 v33, v246 offset:10608
	ds_read_b32 v66, v244 offset:0
	ds_read_b32 v67, v244 offset:132
	ds_read_b32 v68, v244 offset:264
	ds_read_b32 v69, v244 offset:396
	ds_read_b32 v50, v246 offset:8768
	ds_read_b32 v51, v246 offset:9040
	ds_read_b32 v52, v246 offset:9312
	ds_read_b32 v53, v246 offset:9584
	ds_read_b32 v54, v246 offset:9856
	ds_read_b32 v55, v246 offset:10128
	ds_read_b32 v56, v246 offset:10400
	ds_read_b32 v57, v246 offset:10672
	ds_read_b32 v70, v244 offset:2112
	ds_read_b32 v71, v244 offset:2244
	ds_read_b32 v72, v244 offset:2376
	ds_read_b32 v73, v244 offset:2508
	ds_read_b32 v58, v246 offset:8832
	ds_read_b32 v59, v246 offset:9104
	ds_read_b32 v60, v246 offset:9376
	ds_read_b32 v61, v246 offset:9648
	ds_read_b32 v62, v246 offset:9920
	ds_read_b32 v63, v246 offset:10192
	ds_read_b32 v64, v246 offset:10464
	ds_read_b32 v65, v246 offset:10736
	ds_read_b32 v74, v244 offset:4224
	ds_read_b32 v75, v244 offset:4356
	ds_read_b32 v76, v244 offset:4488
	ds_read_b32 v77, v244 offset:4620
	s_waitcnt lgkmcnt(0)
	v_mul_f32_e32 v26, v42, v26
	v_mul_f32_e32 v27, v43, v27
	v_mul_f32_e32 v28, v44, v28
	v_mul_f32_e32 v29, v45, v29
	v_mul_f32_e32 v30, v46, v30
	v_mul_f32_e32 v31, v47, v31
	v_mul_f32_e32 v32, v48, v32
	v_mul_f32_e32 v33, v49, v33
	v_mul_f32_e32 v66, v78, v66
	v_mul_f32_e32 v67, v78, v67
	v_mul_f32_e32 v68, v78, v68
	v_mul_f32_e32 v69, v78, v69
	v_mul_f32_e32 v50, v42, v50
	v_mul_f32_e32 v51, v43, v51
	v_mul_f32_e32 v52, v44, v52
	v_mul_f32_e32 v53, v45, v53
	v_mul_f32_e32 v54, v46, v54
	v_mul_f32_e32 v55, v47, v55
	v_mul_f32_e32 v56, v48, v56
	v_mul_f32_e32 v57, v49, v57
	v_mul_f32_e32 v70, v78, v70
	v_mul_f32_e32 v71, v78, v71
	v_mul_f32_e32 v72, v78, v72
	v_mul_f32_e32 v73, v78, v73
	v_mul_f32_e32 v58, v42, v58
	v_mul_f32_e32 v59, v43, v59
	v_mul_f32_e32 v60, v44, v60
	v_mul_f32_e32 v61, v45, v61
	v_mul_f32_e32 v62, v46, v62
	v_mul_f32_e32 v63, v47, v63
	v_mul_f32_e32 v64, v48, v64
	v_mul_f32_e32 v65, v49, v65
	v_mul_f32_e32 v74, v78, v74
	v_mul_f32_e32 v75, v78, v75
	v_mul_f32_e32 v76, v78, v76
	v_mul_f32_e32 v77, v78, v77
	s_nop 1
	v_mfma_f32_16x16x4_f32 v[66:69], v26, v34, v[66:69]
	v_mfma_f32_16x16x4_f32 v[70:73], v50, v34, v[70:73]
	v_mfma_f32_16x16x4_f32 v[74:77], v58, v34, v[74:77]
	v_mfma_f32_16x16x4_f32 v[66:69], v27, v35, v[66:69]
	v_mfma_f32_16x16x4_f32 v[70:73], v51, v35, v[70:73]
	v_mfma_f32_16x16x4_f32 v[74:77], v59, v35, v[74:77]
	v_mfma_f32_16x16x4_f32 v[66:69], v28, v36, v[66:69]
	v_mfma_f32_16x16x4_f32 v[70:73], v52, v36, v[70:73]
	v_mfma_f32_16x16x4_f32 v[74:77], v60, v36, v[74:77]
	v_mfma_f32_16x16x4_f32 v[66:69], v29, v37, v[66:69]
	v_mfma_f32_16x16x4_f32 v[70:73], v53, v37, v[70:73]
	v_mfma_f32_16x16x4_f32 v[74:77], v61, v37, v[74:77]
	v_mfma_f32_16x16x4_f32 v[66:69], v30, v38, v[66:69]
	v_mfma_f32_16x16x4_f32 v[70:73], v54, v38, v[70:73]
	v_mfma_f32_16x16x4_f32 v[74:77], v62, v38, v[74:77]
	v_mfma_f32_16x16x4_f32 v[66:69], v31, v39, v[66:69]
	v_mfma_f32_16x16x4_f32 v[70:73], v55, v39, v[70:73]
	v_mfma_f32_16x16x4_f32 v[74:77], v63, v39, v[74:77]
	v_mfma_f32_16x16x4_f32 v[66:69], v32, v40, v[66:69]
	v_mfma_f32_16x16x4_f32 v[70:73], v56, v40, v[70:73]
	v_mfma_f32_16x16x4_f32 v[74:77], v64, v40, v[74:77]
	v_mfma_f32_16x16x4_f32 v[66:69], v33, v41, v[66:69]
	v_mfma_f32_16x16x4_f32 v[70:73], v57, v41, v[70:73]
	v_mfma_f32_16x16x4_f32 v[74:77], v65, v41, v[74:77]
	s_nop 7
	s_nop 3
	ds_write_b32 v244, v66 offset:0
	ds_write_b32 v244, v67 offset:132
	ds_write_b32 v244, v68 offset:264
	ds_write_b32 v244, v69 offset:396
	ds_write_b32 v244, v70 offset:2112
	ds_write_b32 v244, v71 offset:2244
	ds_write_b32 v244, v72 offset:2376
	ds_write_b32 v244, v73 offset:2508
	ds_write_b32 v244, v74 offset:4224
	ds_write_b32 v244, v75 offset:4356
	ds_write_b32 v244, v76 offset:4488
	ds_write_b32 v244, v77 offset:4620
